# layer-0 WO residual epilogue (input-tensor residual) as a 12-deep rolling pipeline with counted vmcnt
# baseline (speedup 1.0000x reference)
.LBB0_290:
	s_lshl_b64 s[0:1], s[0:1], 2
	v_lshl_or_b32 v172, s83, 8, v179
	s_add_u32 s0, s65, s0
	s_addc_u32 s1, s70, s1
	v_ashrrev_i32_e32 v173, 31, v172
	v_lshl_add_u64 v[128:129], v[172:173], 2, s[0:1]
	s_lshl_b32 s0, s16, 2
	s_add_i32 s0, s44, s0
	v_mov_b32_e32 v177, s0
	ds_read2_b32 v[130:131], v177 offset1:1
	v_lshl_add_u32 v184, s82, 8, v174
	v_ashrrev_i32_e32 v185, 31, v184
	v_lshlrev_b64 v[132:133], 10, v[184:185]
	s_mov_b32 s16, 0xffc00000
	v_lshl_add_u64 v[170:171], v[132:133], 0, v[172:173]
	s_mov_b32 s17, -1
	s_waitcnt lgkmcnt(0)
	v_readfirstlane_b32 s0, v130
	v_readfirstlane_b32 s1, v131
	v_lshl_add_u64 v[132:133], v[170:171], 0, s[16:17]
	v_mov_b32_e32 v130, s0
	v_mov_b32_e32 v131, s1
	v_cndmask_b32_e64 v133, v133, v171, s[40:41]
	v_cndmask_b32_e64 v132, v132, v170, s[40:41]
	v_lshl_add_u64 v[186:187], v[132:133], 2, v[130:131]
	global_load_dwordx4 v[180:183], v[186:187], off
	global_load_dwordx4 v[140:143], v[128:129], off
	global_load_dwordx4 v[136:139], v[128:129], off offset:64
	global_load_dwordx4 v[132:135], v[128:129], off offset:128
	s_nop 0
	global_load_dwordx4 v[128:131], v[128:129], off offset:192
	v_lshl_add_u64 v[190:191], v[170:171], 2, s[2:3]
	s_and_b64 vcc, exec, s[38:39]
	global_load_dwordx4 v[196:199], v[186:187], off offset:64
	global_load_dwordx4 v[200:203], v[186:187], off offset:128
	global_load_dwordx4 v[204:207], v[186:187], off offset:192
	s_mov_b64 s[0:1], 0x10000
	v_lshl_add_u64 v[192:193], v[186:187], 0, s[0:1]
	global_load_dwordx4 v[208:211], v[192:193], off
	global_load_dwordx4 v[212:215], v[192:193], off offset:64
	global_load_dwordx4 v[216:219], v[192:193], off offset:128
	global_load_dwordx4 v[220:223], v[192:193], off offset:192
	s_mov_b64 s[0:1], 0x20000
	v_lshl_add_u64 v[192:193], v[186:187], 0, s[0:1]
	global_load_dwordx4 v[224:227], v[192:193], off
	global_load_dwordx4 v[228:231], v[192:193], off offset:64
	global_load_dwordx4 v[232:235], v[192:193], off offset:128
	global_load_dwordx4 v[236:239], v[192:193], off offset:192
	s_waitcnt vmcnt(11)
	v_pk_fma_f32 v[126:127], v[126:127], v[142:143], v[182:183]
	v_pk_fma_f32 v[124:125], v[124:125], v[140:141], v[180:181]
	global_store_dwordx4 v[190:191], v[124:127], off
	s_mov_b64 s[0:1], 0x30000
	v_lshl_add_u64 v[192:193], v[186:187], 0, s[0:1]
	global_load_dwordx4 v[180:183], v[192:193], off
	s_waitcnt vmcnt(12)
	v_pk_fma_f32 v[122:123], v[122:123], v[138:139], v[198:199]
	v_pk_fma_f32 v[120:121], v[120:121], v[136:137], v[196:197]
	global_store_dwordx4 v[190:191], v[120:123], off offset:64
	global_load_dwordx4 v[196:199], v[192:193], off offset:64
	s_waitcnt vmcnt(13)
	v_pk_fma_f32 v[118:119], v[118:119], v[134:135], v[202:203]
	v_pk_fma_f32 v[116:117], v[116:117], v[132:133], v[200:201]
	global_store_dwordx4 v[190:191], v[116:119], off offset:128
	global_load_dwordx4 v[200:203], v[192:193], off offset:128
	s_waitcnt vmcnt(14)
	v_pk_fma_f32 v[114:115], v[114:115], v[130:131], v[206:207]
	v_pk_fma_f32 v[112:113], v[112:113], v[128:129], v[204:205]
	global_store_dwordx4 v[190:191], v[112:115], off offset:192
	global_load_dwordx4 v[204:207], v[192:193], off offset:192
	s_waitcnt vmcnt(15)
	v_pk_fma_f32 v[110:111], v[110:111], v[142:143], v[210:211]
	v_pk_fma_f32 v[108:109], v[108:109], v[140:141], v[208:209]
	s_mov_b64 s[0:1], 0x10000
	v_lshl_add_u64 v[194:195], v[190:191], 0, s[0:1]
	global_store_dwordx4 v[194:195], v[108:111], off
	s_mov_b64 s[0:1], 0x80000
	v_lshl_add_u64 v[192:193], v[186:187], 0, s[0:1]
	global_load_dwordx4 v[208:211], v[192:193], off
	s_waitcnt vmcnt(16)
	v_pk_fma_f32 v[106:107], v[106:107], v[138:139], v[214:215]
	v_pk_fma_f32 v[104:105], v[104:105], v[136:137], v[212:213]
	global_store_dwordx4 v[194:195], v[104:107], off offset:64
	global_load_dwordx4 v[212:215], v[192:193], off offset:64
	s_waitcnt vmcnt(17)
	v_pk_fma_f32 v[102:103], v[102:103], v[134:135], v[218:219]
	v_pk_fma_f32 v[100:101], v[100:101], v[132:133], v[216:217]
	global_store_dwordx4 v[194:195], v[100:103], off offset:128
	global_load_dwordx4 v[216:219], v[192:193], off offset:128
	s_waitcnt vmcnt(18)
	v_pk_fma_f32 v[98:99], v[98:99], v[130:131], v[222:223]
	v_pk_fma_f32 v[96:97], v[96:97], v[128:129], v[220:221]
	global_store_dwordx4 v[194:195], v[96:99], off offset:192
	global_load_dwordx4 v[220:223], v[192:193], off offset:192
	s_waitcnt vmcnt(19)
	v_pk_fma_f32 v[94:95], v[94:95], v[142:143], v[226:227]
	v_pk_fma_f32 v[92:93], v[92:93], v[140:141], v[224:225]
	s_mov_b64 s[0:1], 0x20000
	v_lshl_add_u64 v[194:195], v[190:191], 0, s[0:1]
	global_store_dwordx4 v[194:195], v[92:95], off
	s_mov_b64 s[0:1], 0x90000
	v_lshl_add_u64 v[192:193], v[186:187], 0, s[0:1]
	global_load_dwordx4 v[224:227], v[192:193], off
	s_waitcnt vmcnt(20)
	v_pk_fma_f32 v[90:91], v[90:91], v[138:139], v[230:231]
	v_pk_fma_f32 v[88:89], v[88:89], v[136:137], v[228:229]
	global_store_dwordx4 v[194:195], v[88:91], off offset:64
	global_load_dwordx4 v[228:231], v[192:193], off offset:64
	s_waitcnt vmcnt(21)
	v_pk_fma_f32 v[86:87], v[86:87], v[134:135], v[234:235]
	v_pk_fma_f32 v[84:85], v[84:85], v[132:133], v[232:233]
	global_store_dwordx4 v[194:195], v[84:87], off offset:128
	global_load_dwordx4 v[232:235], v[192:193], off offset:128
	s_waitcnt vmcnt(22)
	v_pk_fma_f32 v[82:83], v[82:83], v[130:131], v[238:239]
	v_pk_fma_f32 v[80:81], v[80:81], v[128:129], v[236:237]
	global_store_dwordx4 v[194:195], v[80:83], off offset:192
	global_load_dwordx4 v[236:239], v[192:193], off offset:192
	s_waitcnt vmcnt(22)
	v_pk_fma_f32 v[78:79], v[78:79], v[142:143], v[182:183]
	v_pk_fma_f32 v[76:77], v[76:77], v[140:141], v[180:181]
	s_mov_b64 s[0:1], 0x30000
	v_lshl_add_u64 v[194:195], v[190:191], 0, s[0:1]
	global_store_dwordx4 v[194:195], v[76:79], off
	s_mov_b64 s[0:1], 0xa0000
	v_lshl_add_u64 v[192:193], v[186:187], 0, s[0:1]
	global_load_dwordx4 v[180:183], v[192:193], off
	s_waitcnt vmcnt(22)
	v_pk_fma_f32 v[74:75], v[74:75], v[138:139], v[198:199]
	v_pk_fma_f32 v[72:73], v[72:73], v[136:137], v[196:197]
	global_store_dwordx4 v[194:195], v[72:75], off offset:64
	global_load_dwordx4 v[196:199], v[192:193], off offset:64
	s_waitcnt vmcnt(22)
	v_pk_fma_f32 v[70:71], v[70:71], v[134:135], v[202:203]
	v_pk_fma_f32 v[68:69], v[68:69], v[132:133], v[200:201]
	global_store_dwordx4 v[194:195], v[68:71], off offset:128
	global_load_dwordx4 v[200:203], v[192:193], off offset:128
	s_waitcnt vmcnt(22)
	v_pk_fma_f32 v[66:67], v[66:67], v[130:131], v[206:207]
	v_pk_fma_f32 v[64:65], v[64:65], v[128:129], v[204:205]
	global_store_dwordx4 v[194:195], v[64:67], off offset:192
	global_load_dwordx4 v[204:207], v[192:193], off offset:192
	s_waitcnt vmcnt(22)
	v_pk_fma_f32 v[62:63], v[62:63], v[142:143], v[210:211]
	v_pk_fma_f32 v[60:61], v[60:61], v[140:141], v[208:209]
	s_mov_b64 s[0:1], 0x80000
	v_lshl_add_u64 v[194:195], v[190:191], 0, s[0:1]
	global_store_dwordx4 v[194:195], v[60:63], off
	s_mov_b64 s[0:1], 0xb0000
	v_lshl_add_u64 v[192:193], v[186:187], 0, s[0:1]
	global_load_dwordx4 v[208:211], v[192:193], off
	s_waitcnt vmcnt(22)
	v_pk_fma_f32 v[58:59], v[58:59], v[138:139], v[214:215]
	v_pk_fma_f32 v[56:57], v[56:57], v[136:137], v[212:213]
	global_store_dwordx4 v[194:195], v[56:59], off offset:64
	global_load_dwordx4 v[212:215], v[192:193], off offset:64
	s_waitcnt vmcnt(22)
	v_pk_fma_f32 v[54:55], v[54:55], v[134:135], v[218:219]
	v_pk_fma_f32 v[52:53], v[52:53], v[132:133], v[216:217]
	global_store_dwordx4 v[194:195], v[52:55], off offset:128
	global_load_dwordx4 v[216:219], v[192:193], off offset:128
	s_waitcnt vmcnt(22)
	v_pk_fma_f32 v[50:51], v[50:51], v[130:131], v[222:223]
	v_pk_fma_f32 v[48:49], v[48:49], v[128:129], v[220:221]
	global_store_dwordx4 v[194:195], v[48:51], off offset:192
	global_load_dwordx4 v[220:223], v[192:193], off offset:192
	s_waitcnt vmcnt(22)
	v_pk_fma_f32 v[46:47], v[46:47], v[142:143], v[226:227]
	v_pk_fma_f32 v[44:45], v[44:45], v[140:141], v[224:225]
	s_mov_b64 s[0:1], 0x90000
	v_lshl_add_u64 v[194:195], v[190:191], 0, s[0:1]
	global_store_dwordx4 v[194:195], v[44:47], off
	s_waitcnt vmcnt(21)
	v_pk_fma_f32 v[42:43], v[42:43], v[138:139], v[230:231]
	v_pk_fma_f32 v[40:41], v[40:41], v[136:137], v[228:229]
	global_store_dwordx4 v[194:195], v[40:43], off offset:64
	s_waitcnt vmcnt(20)
	v_pk_fma_f32 v[38:39], v[38:39], v[134:135], v[234:235]
	v_pk_fma_f32 v[36:37], v[36:37], v[132:133], v[232:233]
	global_store_dwordx4 v[194:195], v[36:39], off offset:128
	s_waitcnt vmcnt(19)
	v_pk_fma_f32 v[34:35], v[34:35], v[130:131], v[238:239]
	v_pk_fma_f32 v[32:33], v[32:33], v[128:129], v[236:237]
	global_store_dwordx4 v[194:195], v[32:35], off offset:192
	s_waitcnt vmcnt(18)
	v_pk_fma_f32 v[30:31], v[30:31], v[142:143], v[182:183]
	v_pk_fma_f32 v[28:29], v[28:29], v[140:141], v[180:181]
	s_mov_b64 s[0:1], 0xa0000
	v_lshl_add_u64 v[194:195], v[190:191], 0, s[0:1]
	global_store_dwordx4 v[194:195], v[28:31], off
	s_waitcnt vmcnt(17)
	v_pk_fma_f32 v[26:27], v[26:27], v[138:139], v[198:199]
	v_pk_fma_f32 v[24:25], v[24:25], v[136:137], v[196:197]
	global_store_dwordx4 v[194:195], v[24:27], off offset:64
	s_waitcnt vmcnt(16)
	v_pk_fma_f32 v[22:23], v[22:23], v[134:135], v[202:203]
	v_pk_fma_f32 v[20:21], v[20:21], v[132:133], v[200:201]
	global_store_dwordx4 v[194:195], v[20:23], off offset:128
	s_waitcnt vmcnt(15)
	v_pk_fma_f32 v[18:19], v[18:19], v[130:131], v[206:207]
	v_pk_fma_f32 v[16:17], v[16:17], v[128:129], v[204:205]
	global_store_dwordx4 v[194:195], v[16:19], off offset:192
	s_waitcnt vmcnt(14)
	v_pk_fma_f32 v[14:15], v[14:15], v[142:143], v[210:211]
	v_pk_fma_f32 v[12:13], v[12:13], v[140:141], v[208:209]
	s_mov_b64 s[0:1], 0xb0000
	v_lshl_add_u64 v[194:195], v[190:191], 0, s[0:1]
	global_store_dwordx4 v[194:195], v[12:15], off
	s_waitcnt vmcnt(13)
	v_pk_fma_f32 v[10:11], v[10:11], v[138:139], v[214:215]
	v_pk_fma_f32 v[8:9], v[8:9], v[136:137], v[212:213]
	global_store_dwordx4 v[194:195], v[8:11], off offset:64
	s_waitcnt vmcnt(12)
	v_pk_fma_f32 v[6:7], v[6:7], v[134:135], v[218:219]
	v_pk_fma_f32 v[4:5], v[4:5], v[132:133], v[216:217]
	global_store_dwordx4 v[194:195], v[4:7], off offset:128
	s_waitcnt vmcnt(11)
	v_pk_fma_f32 v[2:3], v[2:3], v[130:131], v[222:223]
	v_pk_fma_f32 v[0:1], v[0:1], v[128:129], v[220:221]
	global_store_dwordx4 v[194:195], v[0:3], off offset:192
	s_mov_b64 s[0:1], -1
	s_and_b64 vcc, exec, s[38:39]
	s_cbranch_vccnz .LBB0_278
	s_andn2_b64 vcc, exec, s[4:5]
	s_cbranch_vccnz .LBB0_277
	s_barrier
	s_branch .LBB0_277
